# attention K/V staging: vmcnt(7..4) instead of vmcnt(3..0) when the younger prefetch set is in flight
# speedup vs baseline: 1.0110x; 1.0110x over previous
; #define ATT_STORE(buf, kr, vr) do { LAS unsigned char* sb_ = lds + (buf) * STAGE; \
;         _Pragma("unroll") for (int i_ = 0; i_ < 2; ++i_) { const int id_ = tid + 512 * i_; \
;             *(LAS u32x4*)(sb_ + ((id_ & 15) >> 3) * KSL + (id_ >> 4) * 144 + (id_ & 7) * 16) = kr[i_]; *(LAS u32x4*)(sb_ + KBUF + (id_ >> 3) * 144 + (id_ & 7) * 16) = vr[i_]; } } while (0)
; __device__ __forceinline__ void unit(const Ctx& C, int xq, int idx, LAS unsigned char* lds) {
;     ...
;     for (int j = 0; j < nt; j += 2) {
;         if (valid && j <= cw) tile(lds, j);
;         if (j + 1 < nt) ATT_STORE(1, krA, vrA);
;         if (j + 3 < nt) ATT_LOAD(j + 3, krA, vrA);
.LBB0_523:
	s_add_i32 s4, s92, -3
	s_cmp_lt_u32 s4, s37
	s_cselect_b64 s[56:57], -1, 0
	s_cmp_ge_u32 s4, s37
	s_cbranch_scc1 .LBB0_525
	s_add_i32 s4, s92, -2
	s_cmp_lt_u32 s4, s37
	s_cbranch_scc1 .Latt_st1_deep
	s_waitcnt vmcnt(3)
	ds_write_b128 v212, v[144:147] offset:36864
	s_waitcnt vmcnt(2)
	ds_write_b128 v213, v[148:151] offset:55296
	s_waitcnt vmcnt(1)
	ds_write_b128 v214, v[152:155] offset:36864
	s_waitcnt vmcnt(0)
	ds_write_b128 v215, v[156:159] offset:55296
	s_branch .LBB0_525
.Latt_st1_deep:
	s_waitcnt vmcnt(7)
	ds_write_b128 v212, v[144:147] offset:36864
	s_waitcnt vmcnt(6)
	ds_write_b128 v213, v[148:151] offset:55296
	s_waitcnt vmcnt(5)
	ds_write_b128 v214, v[152:155] offset:36864
	s_waitcnt vmcnt(4)
	ds_write_b128 v215, v[156:159] offset:55296

; #define ATT_STORE(buf, kr, vr) do { LAS unsigned char* sb_ = lds + (buf) * STAGE; \
;         _Pragma("unroll") for (int i_ = 0; i_ < 2; ++i_) { const int id_ = tid + 512 * i_; \
;             *(LAS u32x4*)(sb_ + ((id_ & 15) >> 3) * KSL + (id_ >> 4) * 144 + (id_ & 7) * 16) = kr[i_]; *(LAS u32x4*)(sb_ + KBUF + (id_ >> 3) * 144 + (id_ & 7) * 16) = vr[i_]; } } while (0)
; __device__ __forceinline__ void unit(const Ctx& C, int xq, int idx, LAS unsigned char* lds) {
;     ...
;         if (j + 2 < nt) ATT_STORE(0, krB, vrB);
;         if (j + 4 < nt) ATT_LOAD(j + 4, krB, vrB);
;         __syncthreads();
.LBB0_544:
	s_add_i32 s4, s92, -1
	s_cmp_lt_u32 s4, s37
	s_cbranch_scc1 .Latt_st0_deep
	s_waitcnt vmcnt(3)
	ds_write_b128 v212, v[160:163]
	s_waitcnt vmcnt(2)
	ds_write_b128 v213, v[164:167] offset:18432
	s_waitcnt vmcnt(1)
	ds_write_b128 v214, v[168:171]
	s_waitcnt vmcnt(0)
	ds_write_b128 v215, v[172:175] offset:18432
	s_branch .Latt_st0_done
.Latt_st0_deep:
	s_waitcnt vmcnt(7)
	ds_write_b128 v212, v[160:163]
	s_waitcnt vmcnt(6)
	ds_write_b128 v213, v[164:167] offset:18432
	s_waitcnt vmcnt(5)
	ds_write_b128 v214, v[168:171]
	s_waitcnt vmcnt(4)
	ds_write_b128 v215, v[172:175] offset:18432
.Latt_st0_done:
	s_cmp_ge_u32 s92, s37
	s_cbranch_scc1 .LBB0_514
.LBB0_545:
	s_and_b64 vcc, exec, s[0:1]
	s_cbranch_vccnz .LBB0_512
	s_cmp_gt_u32 s93, 11
	s_cbranch_scc1 .LBB0_549
	s_lshl_b32 s4, s91, 6
	s_addk_i32 s4, 0x100
	s_lshl_b64 s[56:57], s[4:5], 11
	s_add_u32 s60, s87, s56
	s_addc_u32 s61, s88, s57
	s_lshl_b64 s[56:57], s[4:5], 1
	s_add_u32 s62, s89, s56
	s_addc_u32 s63, s90, s57
	s_mov_b64 s[56:57], 0x400
	s_mov_b64 s[58:59], 0x400
	s_branch .LBB0_513
